# attention tile loop: back edge rotated (barrier is the loop head; exit test, loop-carried moves and next LDS address moved in front of it) (lever 7.11)
# baseline (speedup 1.0000x reference)
; #define LOAD_TILE(ti, kreg, vreg) do { const int k0_ = TILE_K0(ti); const size_t grow_ = ((ti) < 4) ? (size_t)(M_ + b * LCTX + k0_) : (size_t)(b * SEQ + k0_); \
;         kreg = *(const u32x4*)(QKV + (grow_ + krow) * NQKV + 1024 + kvh * 64 + 8 * kch); vreg = *(const u32x4*)(QKV + (grow_ + lane) * NQKV + 1280 + kvh * 64 + 8 * w); } while (0)
; #define LOAD_TILE(ti, kreg, vreg) do { const int k0_ = TILE_K0(ti); const size_t grow_ = ((ti) < 4) ? (size_t)(M_ + b * LCTX + k0_) : (size_t)(b * SEQ + k0_); \
;         kreg = *(const u32x4*)(QKV + (grow_ + krow) * NQKV + 1024 + kvh * 64 + 8 * kch); vreg = *(const u32x4*)(QKV + (grow_ + lane) * NQKV + 1280 + kvh * 64 + 8 * w); } while (0)
; #define STAGE_NEXT(ti, vnext) do { if ((ti) + 1 < ntiles) STORE_TILE(((ti) + 1) & 1, vnext); \
;         kreg = kreg2; vreg = vreg2; kreg2 = kreg3; vreg2 = vreg3; \
;         if ((ti) + 4 < ntiles) LOAD_TILE((ti) + 4, kreg3, vreg3); } while (0)
;     ...
;         bf16x8 pa[4];
;         LOAD_TILE(0, kreg, vreg); STORE_TILE(0, 0); LOAD_TILE(1, kreg, vreg); LOAD_TILE(2, kreg2, vreg2); LOAD_TILE(3, kreg3, vreg3); __syncthreads();
;         {
;             QK_MAX(0, 0)
;             EXP_PACK();
;             if (resc) { _Pragma("unroll") for (int r = 0; r < 16; ++r) { o0[r] *= fres; o1[r] *= fres; } }
;             STAGE_NEXT(0, 1);
;             __syncthreads();
;         }
;         int vprev = 0, vcur = 1;
.LBB0_506:
	v_exp_f32_e32 v1, v18
	v_exp_f32_e32 v46, v2
	v_exp_f32_e32 v47, v19
	v_exp_f32_e32 v48, v3
	v_exp_f32_e32 v49, v20
	v_add_f32_e32 v2, v46, v1
	v_exp_f32_e32 v50, v4
	v_add_f32_e32 v2, 0, v2
	v_add_f32_e32 v3, v48, v47
	v_exp_f32_e32 v51, v21
	v_exp_f32_e32 v52, v5
	v_add_f32_e32 v18, v3, v2
	v_exp_f32_e32 v3, v22
	v_exp_f32_e32 v5, v6
	v_exp_f32_e32 v2, v23
	v_exp_f32_e32 v4, v7
	v_add_f32_e32 v19, v50, v49
	v_add_f32_e32 v6, v19, v18
	v_add_f32_e32 v7, v52, v51
	v_add_f32_e32 v18, v7, v6
	v_pk_add_f32 v[6:7], v[4:5], v[2:3]
	v_exp_f32_e32 v19, v24
	v_add_f32_e32 v7, v7, v18
	v_exp_f32_e32 v21, v8
	v_exp_f32_e32 v18, v25
	v_exp_f32_e32 v20, v9
	v_add_f32_e32 v8, v6, v7
	v_exp_f32_e32 v9, v26
	v_exp_f32_e32 v23, v10
	v_pk_add_f32 v[6:7], v[20:21], v[18:19]
	v_exp_f32_e32 v22, v11
	v_add_f32_e32 v7, v7, v8
	v_exp_f32_e32 v8, v27
	s_lshl_b32 s8, s25, 6
	s_sub_i32 s25, 0x80, s13
	s_lshl_b32 s56, s38, 6
	s_and_b32 s39, s44, 0x1fc0
	s_ashr_i32 s33, s25, 6
	s_cmpk_lt_u32 s13, 0x80
	v_pk_mov_b32 v[10:11], v[18:19], v[18:19] op_sel:[1,0]
	v_pk_mov_b32 v[18:19], v[20:21], v[20:21] op_sel:[1,0]
	v_add_f32_e32 v20, v6, v7
	v_pk_add_f32 v[6:7], v[22:23], v[8:9]
	s_cselect_b32 s57, s33, 0
	s_sub_i32 s33, 0x2040, s13
	v_add_f32_e32 v7, v7, v20
	v_exp_f32_e32 v21, v28
	v_exp_f32_e32 v25, v12
	v_exp_f32_e32 v20, v29
	v_exp_f32_e32 v24, v13
	s_lshr_b32 s33, s33, 6
	s_cmpk_gt_u32 s13, 0x1f40
	s_cselect_b32 s33, s33, 4
	s_sub_i32 s58, s33, s57
	v_pk_mov_b32 v[12:13], v[22:23], v[22:23] op_sel:[1,0]
	v_add_f32_e32 v22, v6, v7
	v_pk_add_f32 v[6:7], v[24:25], v[20:21]
	s_lshl_b32 s33, s57, 6
	v_add_f32_e32 v7, v7, v22
	v_exp_f32_e32 v23, v30
	v_exp_f32_e32 v27, v14
	v_exp_f32_e32 v22, v31
	v_exp_f32_e32 v26, v15
	s_add_i32 s24, s24, s33
	s_add_i32 s13, s13, s24
	s_add_i32 s40, s13, 0xffffff80
	s_ashr_i32 s41, s40, 31
	v_pk_mov_b32 v[14:15], v[20:21], v[20:21] op_sel:[1,0]
	v_pk_mov_b32 v[20:21], v[24:25], v[24:25] op_sel:[1,0]
	v_add_f32_e32 v24, v6, v7
	v_pk_add_f32 v[6:7], v[26:27], v[22:23]
	v_exp_f32_e32 v29, v16
	v_or_b32_e32 v16, s40, v144
	v_mov_b64_e32 v[30:31], s[4:5]
	v_lshl_add_u64 v[44:45], s[40:41], 0, v[154:155]
	v_add_f32_e32 v7, v7, v24
	v_exp_f32_e32 v25, v32
	v_exp_f32_e32 v24, v33
	v_mad_i64_i32 v[32:33], s[62:63], v16, s46, v[30:31]
	s_lshl_b32 s8, s8, 1
	v_mad_u64_u32 v[30:31], s[40:41], v44, s46, v[30:31]
	v_lshl_add_u64 v[32:33], v[32:33], 0, s[8:9]
	s_mov_b32 s13, s9
	v_mad_i32_i24 v31, v45, s46, v31
	v_lshl_add_u64 v[32:33], v[32:33], 0, s[12:13]
	v_lshl_add_u64 v[30:31], v[30:31], 0, s[8:9]
	v_mov_b32_e32 v165, v147
	v_lshl_add_u64 v[30:31], v[30:31], 0, v[164:165]
	global_load_dwordx4 v[112:115], v[32:33], off offset:2560
	global_load_dwordx4 v[116:119], v[30:31], off offset:2048
	v_exp_f32_e32 v28, v17
	v_pk_mov_b32 v[16:17], v[22:23], v[22:23] op_sel:[1,0]
	v_pk_mov_b32 v[22:23], v[26:27], v[26:27] op_sel:[1,0]
	v_add_f32_e32 v26, v6, v7
	v_pk_add_f32 v[6:7], v[28:29], v[24:25]
	v_cvt_pk_bf16_f32 v130, v16, v17
	v_add_f32_e32 v7, v7, v26
	v_cndmask_b32_e64 v16, v42, 0, s[22:23]
	s_add_i32 s13, s58, 4
	v_pk_mov_b32 v[24:25], v[24:25], v[24:25] op_sel:[1,0]
	v_pk_mov_b32 v[26:27], v[28:29], v[28:29] op_sel:[1,0]
	v_add_f32_e32 v6, v6, v7
	v_mov_b32_e32 v30, v16
	v_mov_b32_e32 v31, v16
	s_add_u32 s22, s42, s8
	v_pk_mov_b32 v[2:3], v[2:3], v[2:3] op_sel:[1,0]
	v_pk_mov_b32 v[4:5], v[4:5], v[4:5] op_sel:[1,0]
	v_pk_mov_b32 v[8:9], v[8:9], v[8:9] op_sel:[1,0]
	v_add_f32_e32 v165, v43, v6
	v_cvt_pk_bf16_f32 v132, v1, v47
	v_cvt_pk_bf16_f32 v131, v24, v25
	v_cvt_pk_bf16_f32 v124, v46, v48
	v_cvt_pk_bf16_f32 v127, v18, v19
	v_cvt_pk_bf16_f32 v121, v20, v21
	v_cvt_pk_bf16_f32 v122, v22, v23
	v_cvt_pk_bf16_f32 v123, v26, v27
	v_mov_b32_e32 v17, v16
	v_mov_b32_e32 v18, v16
	v_mov_b32_e32 v19, v16
	v_mov_b32_e32 v20, v16
	v_mov_b32_e32 v21, v16
	v_mov_b32_e32 v22, v16
	v_mov_b32_e32 v23, v16
	v_mov_b32_e32 v24, v16
	v_mov_b32_e32 v25, v16
	v_mov_b32_e32 v26, v16
	v_mov_b32_e32 v27, v16
	v_mov_b32_e32 v28, v16
	v_mov_b32_e32 v29, v16
	s_waitcnt vmcnt(7)
	ds_write_b128 v177, v[38:41] offset:9216
	s_waitcnt vmcnt(6)
	ds_write_b16 v178, v34 offset:27136
	ds_write_b16_d16_hi v178, v34 offset:27272
	ds_write_b16 v178, v35 offset:27408
	ds_write_b16_d16_hi v178, v35 offset:27544
	ds_write_b16 v178, v36 offset:27680
	ds_write_b16_d16_hi v178, v36 offset:27816
	ds_write_b16 v178, v37 offset:27952
	ds_write_b16_d16_hi v178, v37 offset:28088
	s_addc_u32 s23, s43, 0
	s_add_i32 s24, s24, s39
	v_mov_b64_e32 v[46:47], v[30:31]
	v_ashrrev_i32_e32 v171, 31, v170
	s_mov_b32 s25, 0
	v_cvt_pk_bf16_f32 v133, v49, v51
	v_cvt_pk_bf16_f32 v134, v2, v3
	v_cvt_pk_bf16_f32 v135, v10, v11
	v_cvt_pk_bf16_f32 v128, v8, v9
	v_cvt_pk_bf16_f32 v129, v14, v15
	v_cvt_pk_bf16_f32 v125, v50, v52
	v_cvt_pk_bf16_f32 v126, v4, v5
	v_cvt_pk_bf16_f32 v120, v12, v13
	s_mov_b32 s38, 1
	v_lshl_add_u64 v[172:173], v[158:159], 0, s[8:9]
	s_sub_i32 s24, s24, 64
	v_subrev_u32_e32 v167, s33, v179
	v_mov_b64_e32 v[44:45], v[28:29]
	v_mov_b64_e32 v[42:43], v[26:27]
	v_mov_b64_e32 v[40:41], v[24:25]
	v_mov_b64_e32 v[38:39], v[22:23]
	v_mov_b64_e32 v[36:37], v[20:21]
	v_mov_b64_e32 v[34:35], v[18:19]
	v_mov_b64_e32 v[32:33], v[16:17]
	s_mov_b32 s62, 0
	v_mov_b32_e32 v1, v0
	v_mov_b32_e32 v2, v0
	v_mov_b32_e32 v3, v0
	v_mov_b32_e32 v4, v0
	v_mov_b32_e32 v5, v0
	v_mov_b32_e32 v6, v0
	v_mov_b32_e32 v7, v0
	v_mov_b32_e32 v8, v0
	v_mov_b32_e32 v9, v0
	v_mov_b32_e32 v10, v0
	v_mov_b32_e32 v11, v0
	v_mov_b32_e32 v12, v0
	v_mov_b32_e32 v13, v0
	v_mov_b32_e32 v14, v0
	v_mov_b32_e32 v15, v0
	s_waitcnt lgkmcnt(0)
	s_add_i32 s8, s25, 1
	s_bitcmp1_b32 s8, 0
	s_cselect_b32 s33, 0x2400, 0
	v_add_u32_e32 v153, s33, v145
;     ...
;         for (int ti = 1; ti < ntiles; ++ti) {
;             const int vnext = (vcur == 2) ? 0 : vcur + 1;
;             QK_MAX(ti, ti & 1)
.LBB0_507:
	s_barrier
	ds_read_b128 v[64:67], v153
	ds_read_b128 v[136:139], v153 offset:32
	ds_read_b128 v[140:143], v153 offset:4608
	ds_read_b128 v[182:185], v153 offset:4640
	s_mov_b32 s59, s38
	s_waitcnt lgkmcnt(3)
	v_mfma_f32_32x32x16_bf16 v[48:63], v[64:67], v[80:83], v[0:15]
	s_waitcnt lgkmcnt(2)
	v_mfma_f32_32x32x16_bf16 v[48:63], v[136:139], v[84:87], v[48:63]
	s_cmp_lt_u32 s8, 4
	s_waitcnt lgkmcnt(1)
	v_mfma_f32_32x32x16_bf16 v[64:79], v[140:143], v[80:83], v[0:15]
	ds_read_b128 v[136:139], v153 offset:64
	ds_read_b128 v[140:143], v153 offset:96
	s_waitcnt lgkmcnt(2)
	v_mfma_f32_32x32x16_bf16 v[64:79], v[182:185], v[84:87], v[64:79]
	s_waitcnt lgkmcnt(1)
	v_mfma_f32_32x32x16_bf16 v[48:63], v[136:139], v[96:99], v[48:63]
	ds_read_b128 v[136:139], v153 offset:4672
	ds_read_b128 v[182:185], v153 offset:4704
	s_waitcnt lgkmcnt(1)
	v_mfma_f32_32x32x16_bf16 v[64:79], v[136:139], v[96:99], v[64:79]
	v_mfma_f32_32x32x16_bf16 v[48:63], v[140:143], v[100:103], v[48:63]
	s_waitcnt lgkmcnt(0)
	v_mfma_f32_32x32x16_bf16 v[64:79], v[182:185], v[100:103], v[64:79]
	s_mul_i32 s33, s62, 0x2200
	v_add_u32_e32 v224, s33, v174
	v_add_u32_e32 v225, 0x5800, v224
	v_add_u32_e32 v224, 0x4800, v224
	ds_read2_b64 v[192:195], v224 offset1:2
	ds_read2_b64 v[196:199], v224 offset0:4 offset1:6
	ds_read2_b64 v[200:203], v224 offset0:8 offset1:10
	ds_read2_b64 v[204:207], v224 offset0:12 offset1:14
	ds_read2_b64 v[208:211], v225 offset0:32 offset1:34
	ds_read2_b64 v[212:215], v225 offset0:36 offset1:38
	ds_read2_b64 v[216:219], v225 offset0:40 offset1:42
	ds_read2_b64 v[220:223], v225 offset0:44 offset1:46
	s_cbranch_scc1 .LBB0_514
	s_add_i32 s63, s57, s25
	s_add_i32 s63, s63, 1
	s_cmp_lt_i32 s63, 8
	s_cbranch_scc1 .LBB0_510
	s_cmp_eq_u32 s63, 8
	s_cselect_b64 s[38:39], -1, 0
	s_cbranch_execz .LBB0_511
	s_branch .LBB0_512

; #define STAGE_NEXT(ti, vnext) do { if ((ti) + 1 < ntiles) STORE_TILE(((ti) + 1) & 1, vnext); \
;         kreg = kreg2; vreg = vreg2; kreg2 = kreg3; vreg2 = vreg3; \
;         if ((ti) + 4 < ntiles) LOAD_TILE((ti) + 4, kreg3, vreg3); } while (0)
;     ...
;             EXP_PACK();
; #pragma unroll
;             for (int i_ = 0; i_ < 8; ++i_) { __builtin_amdgcn_sched_group_barrier(0x008, 1, 0); __builtin_amdgcn_sched_group_barrier(0x002, 11, 0); }
;             if (resc) { _Pragma("unroll") for (int r = 0; r < 16; ++r) { o0[r] *= fres; o1[r] *= fres; } }
;             STAGE_NEXT(ti, vnext);
;             vprev = vcur; vcur = vnext;
;             __syncthreads();
;         }
.LBB0_523:
	v_exp_f32_e32 v48, v48
	v_exp_f32_e32 v64, v64
	v_exp_f32_e32 v49, v49
	v_exp_f32_e32 v65, v65
	v_exp_f32_e32 v50, v50
	v_exp_f32_e32 v66, v66
	v_exp_f32_e32 v51, v51
	v_exp_f32_e32 v67, v67
	v_add_f32_e32 v233, v48, v64
	v_exp_f32_e32 v52, v52
	v_exp_f32_e32 v68, v68
	v_add_f32_e32 v234, v49, v65
	v_exp_f32_e32 v53, v53
	v_exp_f32_e32 v69, v69
	v_cvt_pk_bf16_f32 v132, v48, v49
	v_add_f32_e32 v48, 0, v233
	v_add_f32_e32 v235, v50, v66
	v_exp_f32_e32 v54, v54
	v_exp_f32_e32 v70, v70
	v_add_f32_e32 v48, v234, v48
	v_add_f32_e32 v236, v51, v67
	v_exp_f32_e32 v55, v55
	v_exp_f32_e32 v71, v71
	v_add_f32_e32 v48, v235, v48
	v_add_f32_e32 v237, v52, v68
	v_exp_f32_e32 v56, v56
	v_exp_f32_e32 v72, v72
	v_add_f32_e32 v48, v236, v48
	v_add_f32_e32 v238, v53, v69
	v_exp_f32_e32 v57, v57
	v_exp_f32_e32 v73, v73
	v_add_f32_e32 v48, v237, v48
	v_add_f32_e32 v239, v54, v70
	v_exp_f32_e32 v58, v58
	v_exp_f32_e32 v74, v74
	v_add_f32_e32 v48, v238, v48
	v_add_f32_e32 v240, v55, v71
	v_exp_f32_e32 v59, v59
	v_exp_f32_e32 v75, v75
	v_add_f32_e32 v48, v239, v48
	v_add_f32_e32 v153, v56, v72
	v_exp_f32_e32 v60, v60
	v_exp_f32_e32 v76, v76
	v_add_f32_e32 v48, v240, v48
	v_add_f32_e32 v182, v57, v73
	v_exp_f32_e32 v61, v61
	v_exp_f32_e32 v77, v77
	v_add_f32_e32 v48, v153, v48
	v_add_f32_e32 v183, v58, v74
	v_exp_f32_e32 v62, v62
	v_exp_f32_e32 v78, v78
	v_add_f32_e32 v48, v182, v48
	v_add_f32_e32 v184, v59, v75
	v_exp_f32_e32 v63, v63
	v_exp_f32_e32 v79, v79
	v_add_f32_e32 v48, v183, v48
	v_add_f32_e32 v185, v60, v76
	v_add_f32_e32 v48, v184, v48
	v_add_f32_e32 v186, v61, v77
	v_add_f32_e32 v48, v185, v48
	v_add_f32_e32 v187, v62, v78
	v_add_f32_e32 v48, v186, v48
	v_add_f32_e32 v188, v63, v79
	v_add_f32_e32 v48, v187, v48
	v_add_f32_e32 v48, v188, v48
	s_add_i32 s24, s24, 64
	v_cvt_pk_bf16_f32 v133, v50, v51
	v_cvt_pk_bf16_f32 v134, v52, v53
	v_cvt_pk_bf16_f32 v135, v54, v55
	v_cvt_pk_bf16_f32 v128, v56, v57
	v_cvt_pk_bf16_f32 v129, v58, v59
	v_cvt_pk_bf16_f32 v130, v60, v61
	v_cvt_pk_bf16_f32 v131, v62, v63
	v_cvt_pk_bf16_f32 v124, v64, v65
	v_cvt_pk_bf16_f32 v125, v66, v67
	v_cvt_pk_bf16_f32 v126, v68, v69
	v_cvt_pk_bf16_f32 v127, v70, v71
	v_cvt_pk_bf16_f32 v120, v72, v73
	v_cvt_pk_bf16_f32 v121, v74, v75
	v_cvt_pk_bf16_f32 v122, v76, v77
	v_cvt_pk_bf16_f32 v123, v78, v79
	v_add_f32_e32 v165, v165, v48
	s_cmp_eq_u32 s13, s8
	v_subrev_u32_e32 v167, 64, v167
	s_waitcnt lgkmcnt(0)
	s_cbranch_scc1 .Lattn_exit
	s_mov_b32 s25, s8
	s_mov_b32 s62, s59
	s_add_i32 s8, s25, 1
	s_bitcmp1_b32 s8, 0
	s_cselect_b32 s33, 0x2400, 0
	v_add_u32_e32 v153, s33, v145
	s_branch .LBB0_507
.Lattn_exit:
	s_barrier
	s_branch .LBB0_502
